# conv-tile cache + LRU priority scheme + carry-segment trims
# baseline (speedup 1.0000x reference)
; #define LAS __attribute__((address_space(3)))
; __device__ __forceinline__ int opaque_tid() { int t = threadIdx.x; asm volatile("" : "+v"(t)); return t; }
; #define LDS_BARRIER() do { asm volatile("s_waitcnt lgkmcnt(0)" ::: "memory"); __builtin_amdgcn_s_barrier(); asm volatile("" ::: "memory"); } while (0)
; __device__ __forceinline__ void lru_strip(LAS unsigned char* lds, const Params& P, int strip, bool dry) {
;     const int tid = opaque_tid();
;     const int b = strip >> 5, h = (strip >> 2) & 7, q = strip & 3;
;     LAS float* CWL = (LAS float*)(lds + 256 * XC_PITCH + 2048 + 64 * XC_PITCH);
;     for (int i = tid; i < 640; i += NTHREADS) { const int k = i >> 7, c = i & 127; CWL[i] = k < 4 ? P.conv_w[k * 1024 + h * 128 + c] : P.conv_b[h * 128 + c]; }
;     LDS_BARRIER();
;     lru_pass<0>(lds, P, b, h, q, dry);
.LBB0_277:
	s_setprio 0
	s_add_u32 s40, s22, 0x7400000
	s_addc_u32 s41, s23, 0
	s_cmp_lg_u32 s101, 0
	s_cbranch_scc1 .Lpp_b_noy
	s_barrier
